# RG-LRU segment scan with DPP row shifts and row broadcasts instead of serialized ds_bpermute chains (on top of the redundant-invalidate removal)
# speedup vs baseline: 1.0157x; 1.0125x over previous
.LBB0_738:
	s_lshl_b32 s68, s7, 7
	v_or_b32_e32 v50, s68, v0
	v_mad_u32_u24 v51, v50, s55, v111
	v_lshl_add_u32 v51, v51, 1, s52
	ds_read_b128 v[56:59], v51
	ds_read_b128 v[60:63], v51 offset:64
	v_mad_u32_u24 v50, v50, s55, v112
	v_lshl_add_u32 v54, v50, 1, s52
	ds_read_b128 v[64:67], v54
	ds_read_b128 v[68:71], v54 offset:64
	s_waitcnt lgkmcnt(0)
	v_mfma_f32_16x16x32_bf16 v[50:53], v[2:5], v[56:59], 0
	v_lshl_add_u32 v54, s7, 8, v152
	s_and_b64 s[4:5], s[96:97], exec
	v_add_u32_e32 v55, 0x400, v54
	s_waitcnt lgkmcnt(2)
	v_mfma_f32_16x16x32_bf16 v[84:87], v[6:9], v[60:63], v[50:53]
	s_cselect_b32 s79, 0, 3
	ds_read2_b32 v[76:77], v55 offset0:64 offset1:80
	s_cmp_eq_u32 s79, 1
	v_add_u32_e32 v50, 0x800, v54
	s_cselect_b64 vcc, -1, 0
	s_cmp_eq_u32 s79, 2
	s_waitcnt lgkmcnt(2)
	v_mfma_f32_16x16x32_bf16 v[78:81], v[2:5], v[64:67], 0
	ds_read2_b32 v[72:73], v50 offset0:64 offset1:80
	v_cndmask_b32_e32 v50, v84, v85, vcc
	s_cselect_b64 s[26:27], -1, 0
	s_cmp_eq_u32 s79, 3
	v_cndmask_b32_e64 v50, v50, v86, s[26:27]
	s_cselect_b64 s[28:29], -1, 0
	v_cndmask_b32_e64 v50, v50, v87, s[28:29]
	s_waitcnt lgkmcnt(0)
	v_add_f32_e32 v50, v76, v50
	v_mfma_f32_16x16x32_bf16 v[88:91], v[6:9], v[68:71], v[78:81]
	v_mul_f32_e32 v50, 0xbfb8aa3b, v50
	v_exp_f32_e32 v50, v50
	ds_read2_b32 v[74:75], v55 offset0:192 offset1:208
	s_and_b64 s[4:5], s[96:97], exec
	s_cselect_b32 s4, 1, 2
	s_nop 2
	v_cndmask_b32_e32 v51, v88, v89, vcc
	v_cndmask_b32_e64 v51, v51, v90, s[26:27]
	v_add_f32_e32 v50, 1.0, v50
	v_cndmask_b32_e64 v51, v51, v91, s[28:29]
	v_rcp_f32_e32 v50, v50
	s_waitcnt lgkmcnt(0)
	v_add_f32_e32 v51, v74, v51
	v_mul_f32_e32 v51, 0xbfb8aa3b, v51
	v_exp_f32_e32 v51, v51
	v_mul_f32_e32 v50, 0xc1000000, v50
	v_mul_f32_e32 v50, v72, v50
	v_mul_f32_e32 v50, 0x3fb8aa3b, v50
	v_exp_f32_e32 v173, v50
	v_add_f32_e32 v50, 1.0, v51
	v_rcp_f32_e32 v50, v50
	s_cmp_eq_u32 s4, 1
	v_cndmask_b32_e64 v51, v158, v155, s[96:97]
	s_cselect_b64 s[30:31], -1, 0
	s_cmp_eq_u32 s4, 2
	v_mul_f32_e32 v81, v51, v50
	v_cndmask_b32_e64 v50, v84, v85, s[30:31]
	s_cselect_b64 s[34:35], -1, 0
	s_cmp_eq_u32 s4, 3
	v_cndmask_b32_e64 v50, v50, v86, s[34:35]
	s_cselect_b64 s[36:37], -1, 0
	v_cndmask_b32_e64 v50, v50, v87, s[36:37]
	v_add_f32_e32 v50, v76, v50
	v_mul_f32_e32 v50, 0xbfb8aa3b, v50
	v_exp_f32_e32 v50, v50
	v_cndmask_b32_e64 v51, v88, v89, s[30:31]
	v_cndmask_b32_e64 v51, v51, v90, s[34:35]
	v_cndmask_b32_e64 v51, v51, v91, s[36:37]
	v_add_f32_e32 v50, 1.0, v50
	v_rcp_f32_e32 v50, v50
	v_add_f32_e32 v51, v74, v51
	v_fma_f32 v52, -v173, v173, 1.0
	v_mul_f32_e32 v51, 0xbfb8aa3b, v51
	v_sqrt_f32_e32 v79, v52
	v_exp_f32_e32 v52, v51
	s_and_b64 s[38:39], s[96:97], exec
	v_mul_f32_e32 v50, 0xc1000000, v50
	s_cselect_b32 s5, 2, 1
	v_mul_f32_e32 v50, v72, v50
	s_cmp_eq_u32 s5, 1
	v_mul_f32_e32 v50, 0x3fb8aa3b, v50
	s_cselect_b64 s[38:39], -1, 0
	s_cmp_eq_u32 s5, 2
	v_exp_f32_e32 v51, v50
	v_add_f32_e32 v50, 1.0, v52
	v_cndmask_b32_e64 v52, v84, v85, s[38:39]
	s_cselect_b64 s[40:41], -1, 0
	s_cmp_eq_u32 s5, 3
	v_cndmask_b32_e64 v52, v52, v86, s[40:41]
	s_cselect_b64 s[42:43], -1, 0
	v_cndmask_b32_e64 v52, v52, v87, s[42:43]
	v_add_f32_e32 v52, v76, v52
	v_mul_f32_e32 v52, 0xbfb8aa3b, v52
	v_exp_f32_e32 v52, v52
	v_cndmask_b32_e64 v53, v88, v89, s[38:39]
	v_cndmask_b32_e64 v53, v53, v90, s[40:41]
	v_cndmask_b32_e64 v53, v53, v91, s[42:43]
	v_add_f32_e32 v52, 1.0, v52
	v_rcp_f32_e32 v52, v52
	v_add_f32_e32 v53, v74, v53
	v_mul_f32_e32 v53, 0xbfb8aa3b, v53
	v_exp_f32_e32 v53, v53
	v_mul_f32_e32 v52, 0xc1000000, v52
	v_mul_f32_e32 v52, v72, v52
	v_mul_f32_e32 v52, 0x3fb8aa3b, v52
	v_exp_f32_e32 v55, v52
	v_add_f32_e32 v52, 1.0, v53
	v_rcp_f32_e32 v52, v52
	s_and_b64 s[44:45], s[96:97], exec
	s_cselect_b32 s6, 3, 0
	s_cmp_eq_u32 s6, 1
	v_cndmask_b32_e64 v53, v156, v157, s[96:97]
	s_cselect_b64 s[44:45], -1, 0
	s_cmp_eq_u32 s6, 2
	v_mul_f32_e32 v82, v53, v52
	v_cndmask_b32_e64 v52, v84, v85, s[44:45]
	s_cselect_b64 s[46:47], -1, 0
	s_cmp_eq_u32 s6, 3
	v_cndmask_b32_e64 v52, v52, v86, s[46:47]
	s_cselect_b64 s[48:49], -1, 0
	v_cndmask_b32_e64 v52, v52, v87, s[48:49]
	v_add_f32_e32 v52, v76, v52
	v_mul_f32_e32 v52, 0xbfb8aa3b, v52
	v_exp_f32_e32 v52, v52
	v_cndmask_b32_e64 v83, v88, v89, s[44:45]
	v_cndmask_b32_e64 v83, v83, v90, s[46:47]
	v_cndmask_b32_e64 v83, v83, v91, s[48:49]
	v_add_f32_e32 v52, 1.0, v52
	v_rcp_f32_e32 v52, v52
	v_add_f32_e32 v83, v74, v83
	v_mul_f32_e32 v83, 0xbfb8aa3b, v83
	v_exp_f32_e32 v83, v83
	v_mfma_f32_16x16x32_bf16 v[84:87], v[10:13], v[56:59], 0
	v_mul_f32_e32 v52, 0xc1000000, v52
	v_mul_f32_e32 v52, v72, v52
	v_mul_f32_e32 v52, 0x3fb8aa3b, v52
	v_exp_f32_e32 v59, v52
	v_add_f32_e32 v52, 1.0, v83
	v_rcp_f32_e32 v52, v52
	v_mfma_f32_16x16x32_bf16 v[60:63], v[14:17], v[60:63], v[84:87]
	v_cndmask_b32_e64 v53, v155, v158, s[96:97]
	v_fma_f32 v56, -v59, v59, 1.0
	v_mul_f32_e32 v88, v53, v52
	v_mfma_f32_16x16x32_bf16 v[64:67], v[10:13], v[64:67], 0
	v_sqrt_f32_e32 v58, v56
	s_nop 2
	v_cndmask_b32_e32 v52, v60, v61, vcc
	v_cndmask_b32_e64 v52, v52, v62, s[26:27]
	v_cndmask_b32_e64 v52, v52, v63, s[28:29]
	v_add_f32_e32 v52, v76, v52
	v_mfma_f32_16x16x32_bf16 v[64:67], v[14:17], v[68:71], v[64:67]
	v_mul_f32_e32 v52, 0xbfb8aa3b, v52
	v_exp_f32_e32 v52, v52
	v_cndmask_b32_e64 v69, v160, v161, s[96:97]
	v_cndmask_b32_e64 v70, v159, v154, s[96:97]
	v_cndmask_b32_e64 v83, v168, v169, s[96:97]
	s_nop 2
	v_cndmask_b32_e32 v53, v64, v65, vcc
	v_cndmask_b32_e64 v53, v53, v66, s[26:27]
	v_add_f32_e32 v52, 1.0, v52
	v_cndmask_b32_e64 v53, v53, v67, s[28:29]
	v_rcp_f32_e32 v52, v52
	v_add_f32_e32 v53, v74, v53
	v_mul_f32_e32 v53, 0xbfb8aa3b, v53
	v_exp_f32_e32 v53, v53
	v_mul_f32_e32 v52, 0xc1000000, v52
	v_mul_f32_e32 v52, v72, v52
	v_mul_f32_e32 v52, 0x3fb8aa3b, v52
	v_exp_f32_e32 v174, v52
	v_add_f32_e32 v52, 1.0, v53
	v_rcp_f32_e32 v52, v52
	v_cndmask_b32_e64 v53, v154, v159, s[96:97]
	v_fma_f32 v56, -v174, v174, 1.0
	v_sqrt_f32_e32 v85, v56
	v_mul_f32_e32 v87, v53, v52
	v_cndmask_b32_e64 v52, v60, v61, s[30:31]
	v_cndmask_b32_e64 v52, v52, v62, s[34:35]
	v_cndmask_b32_e64 v52, v52, v63, s[36:37]
	v_add_f32_e32 v52, v76, v52
	v_mul_f32_e32 v52, 0xbfb8aa3b, v52
	v_exp_f32_e32 v52, v52
	v_cndmask_b32_e64 v53, v64, v65, s[30:31]
	v_cndmask_b32_e64 v53, v53, v66, s[34:35]
	v_cndmask_b32_e64 v53, v53, v67, s[36:37]
	v_add_f32_e32 v52, 1.0, v52
	v_rcp_f32_e32 v52, v52
	v_add_f32_e32 v53, v74, v53
	v_mul_f32_e32 v53, 0xbfb8aa3b, v53
	v_exp_f32_e32 v56, v53
	v_mul_f32_e32 v52, 0xc1000000, v52
	v_mul_f32_e32 v52, v72, v52
	v_mul_f32_e32 v52, 0x3fb8aa3b, v52
	v_exp_f32_e32 v53, v52
	v_add_f32_e32 v52, 1.0, v56
	v_cndmask_b32_e64 v56, v60, v61, s[38:39]
	v_cndmask_b32_e64 v56, v56, v62, s[40:41]
	v_cndmask_b32_e64 v56, v56, v63, s[42:43]
	v_add_f32_e32 v56, v76, v56
	v_mul_f32_e32 v56, 0xbfb8aa3b, v56
	v_exp_f32_e32 v56, v56
	v_cndmask_b32_e64 v57, v64, v65, s[38:39]
	v_cndmask_b32_e64 v57, v57, v66, s[40:41]
	v_cndmask_b32_e64 v57, v57, v67, s[42:43]
	v_add_f32_e32 v56, 1.0, v56
	v_rcp_f32_e32 v56, v56
	v_add_f32_e32 v57, v74, v57
	v_mul_f32_e32 v57, 0xbfb8aa3b, v57
	v_exp_f32_e32 v68, v57
	v_mul_f32_e32 v56, 0xc1000000, v56
	v_cndmask_b32_e64 v60, v60, v61, s[44:45]
	v_cndmask_b32_e64 v61, v64, v65, s[44:45]
	v_mul_f32_e32 v56, v72, v56
	v_cndmask_b32_e64 v61, v61, v66, s[46:47]
	v_mul_f32_e32 v56, 0x3fb8aa3b, v56
	v_cndmask_b32_e64 v61, v61, v67, s[48:49]
	v_exp_f32_e32 v57, v56
	v_add_f32_e32 v56, 1.0, v68
	v_add_f32_e32 v61, v74, v61
	v_rcp_f32_e32 v68, v56
	v_mul_f32_e32 v61, 0xbfb8aa3b, v61
	v_exp_f32_e32 v71, v61
	v_or_b32_e32 v61, s68, v153
	v_cndmask_b32_e64 v60, v60, v62, s[46:47]
	v_mad_u32_u24 v62, v61, s55, v111
	v_lshl_add_u32 v62, v62, 1, s52
	v_mul_f32_e32 v106, v69, v68
	ds_read_b128 v[66:69], v62
	v_mad_u32_u24 v61, v61, s55, v112
	v_lshl_add_u32 v61, v61, 1, s52
	ds_read_b128 v[90:93], v61
	ds_read_b128 v[94:97], v62 offset:64
	v_cndmask_b32_e64 v60, v60, v63, s[48:49]
	s_waitcnt lgkmcnt(0)
	v_mfma_f32_16x16x32_bf16 v[62:65], v[2:5], v[66:69], 0
	ds_read_b128 v[98:101], v61 offset:64
	v_add_f32_e32 v60, v76, v60
	v_mul_f32_e32 v60, 0xbfb8aa3b, v60
	s_waitcnt lgkmcnt(1)
	v_mfma_f32_16x16x32_bf16 v[176:179], v[6:9], v[94:97], v[62:65]
	v_exp_f32_e32 v60, v60
	v_rcp_f32_e32 v78, v50
	v_fma_f32 v50, -v51, v51, 1.0
	v_mfma_f32_16x16x32_bf16 v[102:105], v[2:5], v[90:93], 0
	v_add_f32_e32 v60, 1.0, v60
	s_nop 2
	v_cndmask_b32_e32 v62, v176, v177, vcc
	v_cndmask_b32_e64 v62, v62, v178, s[26:27]
	v_cndmask_b32_e64 v62, v62, v179, s[28:29]
	v_add_f32_e32 v62, v77, v62
	s_waitcnt lgkmcnt(0)
	v_mfma_f32_16x16x32_bf16 v[102:105], v[6:9], v[98:101], v[102:105]
	v_mul_f32_e32 v62, 0xbfb8aa3b, v62
	v_exp_f32_e32 v62, v62
	v_rcp_f32_e32 v60, v60
	v_mfma_f32_16x16x32_bf16 v[90:93], v[10:13], v[90:93], 0
	v_sqrt_f32_e32 v50, v50
	s_nop 2
	v_cndmask_b32_e32 v63, v102, v103, vcc
	v_cndmask_b32_e64 v63, v63, v104, s[26:27]
	v_add_f32_e32 v62, 1.0, v62
	v_cndmask_b32_e64 v63, v63, v105, s[28:29]
	v_rcp_f32_e32 v62, v62
	v_add_f32_e32 v63, v75, v63
	v_mul_f32_e32 v63, 0xbfb8aa3b, v63
	v_exp_f32_e32 v63, v63
	v_mul_f32_e32 v62, 0xc1000000, v62
	v_mul_f32_e32 v62, v73, v62
	v_mul_f32_e32 v62, 0x3fb8aa3b, v62
	v_exp_f32_e32 v175, v62
	v_add_f32_e32 v62, 1.0, v63
	v_rcp_f32_e32 v62, v62
	v_cndmask_b32_e64 v63, v166, v163, s[96:97]
	v_fma_f32 v64, -v175, v175, 1.0
	v_sqrt_f32_e32 v181, v64
	v_mul_f32_e32 v183, v63, v62
	v_cndmask_b32_e64 v62, v176, v177, s[30:31]
	v_cndmask_b32_e64 v62, v62, v178, s[34:35]
	v_cndmask_b32_e64 v62, v62, v179, s[36:37]
	v_add_f32_e32 v62, v77, v62
	v_mul_f32_e32 v62, 0xbfb8aa3b, v62
	v_exp_f32_e32 v62, v62
	v_cndmask_b32_e64 v63, v102, v103, s[30:31]
	v_cndmask_b32_e64 v63, v63, v104, s[34:35]
	v_cndmask_b32_e64 v63, v63, v105, s[36:37]
	v_add_f32_e32 v62, 1.0, v62
	v_rcp_f32_e32 v62, v62
	v_add_f32_e32 v63, v75, v63
	v_mul_f32_e32 v63, 0xbfb8aa3b, v63
	v_exp_f32_e32 v64, v63
	v_mul_f32_e32 v62, 0xc1000000, v62
	v_mul_f32_e32 v62, v73, v62
	v_mul_f32_e32 v62, 0x3fb8aa3b, v62
	v_exp_f32_e32 v63, v62
	v_add_f32_e32 v62, 1.0, v64
	v_cndmask_b32_e64 v64, v176, v177, s[38:39]
	v_cndmask_b32_e64 v64, v64, v178, s[40:41]
	v_cndmask_b32_e64 v64, v64, v179, s[42:43]
	v_add_f32_e32 v64, v77, v64
	v_mul_f32_e32 v64, 0xbfb8aa3b, v64
	v_mul_f32_e32 v60, 0xc1000000, v60
	v_exp_f32_e32 v64, v64
	v_mul_f32_e32 v60, v72, v60
	v_mul_f32_e32 v60, 0x3fb8aa3b, v60
	v_exp_f32_e32 v61, v60
	v_add_f32_e32 v60, 1.0, v71
	v_cndmask_b32_e64 v65, v102, v103, s[38:39]
	v_rcp_f32_e32 v71, v60
	v_cndmask_b32_e64 v65, v65, v104, s[40:41]
	v_add_f32_e32 v64, 1.0, v64
	v_cndmask_b32_e64 v65, v65, v105, s[42:43]
	v_rcp_f32_e32 v64, v64
	v_add_f32_e32 v65, v75, v65
	v_mul_f32_e32 v65, 0xbfb8aa3b, v65
	v_mul_f32_e32 v74, v70, v71
	v_exp_f32_e32 v70, v65
	v_mul_f32_e32 v64, 0xc1000000, v64
	v_mul_f32_e32 v64, v73, v64
	v_mul_f32_e32 v64, 0x3fb8aa3b, v64
	v_exp_f32_e32 v65, v64
	v_add_f32_e32 v64, 1.0, v70
	v_rcp_f32_e32 v70, v64
	v_cndmask_b32_e64 v71, v164, v165, s[96:97]
	v_cndmask_b32_e64 v72, v102, v103, s[44:45]
	v_cndmask_b32_e64 v72, v72, v104, s[46:47]
	v_mul_f32_e32 v76, v71, v70
	v_cndmask_b32_e64 v70, v176, v177, s[44:45]
	v_cndmask_b32_e64 v70, v70, v178, s[46:47]
	v_cndmask_b32_e64 v70, v70, v179, s[48:49]
	v_add_f32_e32 v70, v77, v70
	v_mul_f32_e32 v70, 0xbfb8aa3b, v70
	v_exp_f32_e32 v70, v70
	v_cndmask_b32_e64 v72, v72, v105, s[48:49]
	v_add_f32_e32 v72, v75, v72
	v_mul_f32_e32 v72, 0xbfb8aa3b, v72
	v_add_f32_e32 v70, 1.0, v70
	v_rcp_f32_e32 v70, v70
	v_exp_f32_e32 v72, v72
	v_mfma_f32_16x16x32_bf16 v[102:105], v[10:13], v[66:69], 0
	v_cndmask_b32_e64 v71, v163, v166, s[96:97]
	v_mul_f32_e32 v66, 0xc1000000, v70
	v_mul_f32_e32 v66, v73, v66
	v_mul_f32_e32 v66, 0x3fb8aa3b, v66
	v_exp_f32_e32 v69, v66
	v_add_f32_e32 v66, 1.0, v72
	v_rcp_f32_e32 v66, v66
	v_mfma_f32_16x16x32_bf16 v[94:97], v[14:17], v[94:97], v[102:105]
	v_fma_f32 v67, -v69, v69, 1.0
	v_sqrt_f32_e32 v68, v67
	v_mul_f32_e32 v178, v71, v66
	v_mfma_f32_16x16x32_bf16 v[90:93], v[14:17], v[98:101], v[90:93]
	v_rcp_f32_e32 v180, v62
	s_nop 2
	v_cndmask_b32_e32 v66, v94, v95, vcc
	v_cndmask_b32_e64 v66, v66, v96, s[26:27]
	v_cndmask_b32_e64 v66, v66, v97, s[28:29]
	v_add_f32_e32 v66, v77, v66
	v_mul_f32_e32 v66, 0xbfb8aa3b, v66
	v_exp_f32_e32 v66, v66
	v_cndmask_b32_e32 v67, v90, v91, vcc
	v_cndmask_b32_e64 v67, v67, v92, s[26:27]
	v_cndmask_b32_e64 v67, v67, v93, s[28:29]
	v_add_f32_e32 v66, 1.0, v66
	v_rcp_f32_e32 v66, v66
	v_add_f32_e32 v67, v75, v67
	v_mul_f32_e32 v67, 0xbfb8aa3b, v67
	v_exp_f32_e32 v67, v67
	v_mul_f32_e32 v66, 0xc1000000, v66
	v_mul_f32_e32 v66, v73, v66
	v_mul_f32_e32 v66, 0x3fb8aa3b, v66
	v_exp_f32_e32 v176, v66
	v_add_f32_e32 v66, 1.0, v67
	v_rcp_f32_e32 v66, v66
	v_cndmask_b32_e64 v67, v162, v167, s[96:97]
	v_fma_f32 v70, -v176, v176, 1.0
	v_sqrt_f32_e32 v185, v70
	v_mul_f32_e32 v187, v67, v66
	v_cndmask_b32_e64 v66, v94, v95, s[30:31]
	v_cndmask_b32_e64 v66, v66, v96, s[34:35]
	v_cndmask_b32_e64 v66, v66, v97, s[36:37]
	v_add_f32_e32 v66, v77, v66
	v_mul_f32_e32 v66, 0xbfb8aa3b, v66
	v_exp_f32_e32 v66, v66
	v_cndmask_b32_e64 v67, v90, v91, s[30:31]
	v_cndmask_b32_e64 v67, v67, v92, s[34:35]
	v_cndmask_b32_e64 v67, v67, v93, s[36:37]
	v_add_f32_e32 v66, 1.0, v66
	v_rcp_f32_e32 v66, v66
	v_add_f32_e32 v67, v75, v67
	v_mul_f32_e32 v67, 0xbfb8aa3b, v67
	v_exp_f32_e32 v70, v67
	v_mul_f32_e32 v66, 0xc1000000, v66
	v_mul_f32_e32 v66, v73, v66
	v_mul_f32_e32 v66, 0x3fb8aa3b, v66
	v_exp_f32_e32 v67, v66
	v_add_f32_e32 v66, 1.0, v70
	v_cndmask_b32_e64 v70, v94, v95, s[38:39]
	v_cndmask_b32_e64 v70, v70, v96, s[40:41]
	v_cndmask_b32_e64 v70, v70, v97, s[42:43]
	v_add_f32_e32 v70, v77, v70
	v_mul_f32_e32 v70, 0xbfb8aa3b, v70
	v_exp_f32_e32 v70, v70
	v_cndmask_b32_e64 v71, v90, v91, s[38:39]
	v_cndmask_b32_e64 v71, v71, v92, s[40:41]
	v_cndmask_b32_e64 v71, v71, v93, s[42:43]
	v_add_f32_e32 v70, 1.0, v70
	v_rcp_f32_e32 v70, v70
	v_add_f32_e32 v71, v75, v71
	v_mul_f32_e32 v71, 0xbfb8aa3b, v71
	v_exp_f32_e32 v72, v71
	v_mul_f32_e32 v70, 0xc1000000, v70
	v_mul_f32_e32 v70, v73, v70
	v_mul_f32_e32 v70, 0x3fb8aa3b, v70
	v_exp_f32_e32 v71, v70
	v_add_f32_e32 v70, 1.0, v72
	v_rcp_f32_e32 v72, v70
	v_fma_f32 v62, -v63, v63, 1.0
	v_cndmask_b32_e64 v80, v157, v156, s[96:97]
	v_fma_f32 v54, -v55, v55, 1.0
	v_mul_f32_e32 v188, v83, v72
	v_cndmask_b32_e64 v72, v94, v95, s[44:45]
	v_cndmask_b32_e64 v72, v72, v96, s[46:47]
	v_cndmask_b32_e64 v72, v72, v97, s[48:49]
	v_add_f32_e32 v72, v77, v72
	v_mul_f32_e32 v72, 0xbfb8aa3b, v72
	v_exp_f32_e32 v72, v72
	v_cndmask_b32_e64 v77, v90, v91, s[44:45]
	v_cndmask_b32_e64 v77, v77, v92, s[46:47]
	v_cndmask_b32_e64 v77, v77, v93, s[48:49]
	v_add_f32_e32 v72, 1.0, v72
	v_rcp_f32_e32 v72, v72
	v_add_f32_e32 v75, v75, v77
	v_mul_f32_e32 v75, 0xbfb8aa3b, v75
	v_exp_f32_e32 v75, v75
	v_mul_f32_e32 v72, 0xc1000000, v72
	v_mul_f32_e32 v72, v73, v72
	v_sqrt_f32_e32 v62, v62
	v_mul_f32_e32 v72, 0x3fb8aa3b, v72
	v_sqrt_f32_e32 v54, v54
	v_exp_f32_e32 v73, v72
	v_add_f32_e32 v72, 1.0, v75
	v_pk_mul_f32 v[98:99], v[80:81], v[78:79]
	v_cndmask_b32_e64 v182, v165, v164, s[96:97]
	v_fma_f32 v64, -v65, v65, 1.0
	v_rcp_f32_e32 v75, v72
	v_pk_mul_f32 v[100:101], v[98:99], v[50:51]
	v_sqrt_f32_e32 v64, v64
	v_pk_fma_f32 v[78:79], v[98:99], v[50:51], v[100:101] op_sel_hi:[1,1,0]
	v_pk_mul_f32 v[90:91], v[182:183], v[180:181]
	v_mov_b32_e32 v83, v79
	v_pk_mul_f32 v[92:93], v[90:91], v[62:63]
	v_cndmask_b32_e64 v77, v167, v162, s[96:97]
	v_pk_mul_f32 v[102:103], v[82:83], v[54:55]
	v_pk_fma_f32 v[80:81], v[90:91], v[62:63], v[92:93] op_sel_hi:[1,1,0]
	v_mul_f32_e32 v190, v77, v75
	v_pk_fma_f32 v[78:79], v[82:83], v[54:55], v[102:103] op_sel_hi:[1,1,0]
	v_mov_b32_e32 v77, v81
	v_rcp_f32_e32 v84, v52
	v_fma_f32 v52, -v53, v53, 1.0
	v_mov_b32_e32 v89, v79
	v_pk_mul_f32 v[94:95], v[76:77], v[64:65]
	v_sqrt_f32_e32 v52, v52
	v_mul_f32_e32 v50, v173, v51
	v_pk_mul_f32 v[104:105], v[88:89], v[58:59]
	v_pk_fma_f32 v[76:77], v[76:77], v[64:65], v[94:95] op_sel_hi:[1,1,0]
	v_mul_f32_e32 v50, v55, v50
	v_pk_fma_f32 v[78:79], v[88:89], v[58:59], v[104:105] op_sel_hi:[1,1,0]
	v_mov_b32_e32 v179, v77
	v_cndmask_b32_e64 v86, v161, v160, s[96:97]
	v_fma_f32 v56, -v57, v57, 1.0
	v_mul_f32_e32 v78, v59, v50
	v_mul_f32_e32 v50, v175, v63
	v_pk_mul_f32 v[96:97], v[178:179], v[68:69]
	v_sqrt_f32_e32 v56, v56
	v_mul_f32_e32 v50, v65, v50
	v_pk_fma_f32 v[76:77], v[178:179], v[68:69], v[96:97] op_sel_hi:[1,1,0]
	v_pk_mul_f32 v[82:83], v[86:87], v[84:85]
	v_mul_f32_e32 v76, v69, v50
	v_pk_mul_f32 v[84:85], v[82:83], v[52:53]
	v_fma_f32 v60, -v61, v61, 1.0
	ds_write2_b64 v135, v[78:79], v[76:77] offset1:16
	v_pk_fma_f32 v[76:77], v[82:83], v[52:53], v[84:85] op_sel_hi:[1,1,0]
	v_sqrt_f32_e32 v60, v60
	v_mov_b32_e32 v107, v77
	v_rcp_f32_e32 v184, v66
	v_fma_f32 v66, -v67, v67, 1.0
	v_pk_mul_f32 v[86:87], v[106:107], v[56:57]
	v_sqrt_f32_e32 v66, v66
	v_pk_fma_f32 v[76:77], v[106:107], v[56:57], v[86:87] op_sel_hi:[1,1,0]
	v_cndmask_b32_e64 v186, v169, v168, s[96:97]
	v_mov_b32_e32 v75, v77
	v_fma_f32 v70, -v71, v71, 1.0
	v_pk_mul_f32 v[88:89], v[74:75], v[60:61]
	v_sqrt_f32_e32 v70, v70
	v_pk_fma_f32 v[106:107], v[74:75], v[60:61], v[88:89] op_sel_hi:[1,1,0]
	v_pk_mul_f32 v[74:75], v[186:187], v[184:185]
	v_fma_f32 v72, -v73, v73, 1.0
	v_pk_mul_f32 v[76:77], v[74:75], v[66:67]
	v_sqrt_f32_e32 v72, v72
	v_pk_fma_f32 v[78:79], v[74:75], v[66:67], v[76:77] op_sel_hi:[1,1,0]
	v_mul_f32_e32 v50, v174, v53
	v_mov_b32_e32 v189, v79
	v_pk_mul_f32 v[78:79], v[188:189], v[70:71]
	v_mul_f32_e32 v50, v57, v50
	v_pk_fma_f32 v[80:81], v[188:189], v[70:71], v[78:79] op_sel_hi:[1,1,0]
	v_mul_f32_e32 v106, v61, v50
	v_mov_b32_e32 v191, v81
	v_mul_f32_e32 v50, v176, v67
	v_pk_mul_f32 v[80:81], v[190:191], v[72:73]
	v_cndmask_b32_e64 v177, v113, v108, s[96:97]
	v_mul_f32_e32 v50, v71, v50
	v_pk_fma_f32 v[178:179], v[190:191], v[72:73], v[80:81] op_sel_hi:[1,1,0]
	v_mad_u32_u24 v52, v177, s54, v132
	v_mul_f32_e32 v178, v73, v50
	ds_write2_b64 v135, v[106:107], v[178:179] offset0:132 offset1:148
	s_waitcnt lgkmcnt(0)
	s_barrier
	s_lshl_b32 s26, s7, 9
	s_or_b32 s68, s26, s33
	s_lshl_b64 s[26:27], s[68:69], 3
	s_add_u32 s28, s93, s26
	s_addc_u32 s29, s90, s27
	s_or_b32 s7, s7, s91
	s_lshl_b32 s7, s7, 9
	ds_read_b64 v[192:193], v52
	ds_read_b64 v[194:195], v52 offset:8
	ds_read_b64 v[196:197], v52 offset:16
	ds_read_b64 v[198:199], v52 offset:24
	s_waitcnt lgkmcnt(0)
	v_mov_b32_e32 v200, 1.0
	v_mov_b32_e32 v201, 0
	v_mov_b32_e32 v202, 1.0
	v_mov_b32_e32 v203, 0
	v_mov_b32_e32 v204, 1.0
	v_mov_b32_e32 v205, 0
	v_mov_b32_e32 v206, 1.0
	v_mov_b32_e32 v207, 0
	v_fmac_f32_dpp v193, v193, v192 row_shr:1 row_mask:0xf bank_mask:0xf
	v_fmac_f32_dpp v195, v195, v194 row_shr:1 row_mask:0xf bank_mask:0xf
	v_fmac_f32_dpp v197, v197, v196 row_shr:1 row_mask:0xf bank_mask:0xf
	v_fmac_f32_dpp v199, v199, v198 row_shr:1 row_mask:0xf bank_mask:0xf
	v_mul_f32_dpp v192, v192, v192 row_shr:1 row_mask:0xf bank_mask:0xf
	v_mul_f32_dpp v194, v194, v194 row_shr:1 row_mask:0xf bank_mask:0xf
	v_mul_f32_dpp v196, v196, v196 row_shr:1 row_mask:0xf bank_mask:0xf
	v_mul_f32_dpp v198, v198, v198 row_shr:1 row_mask:0xf bank_mask:0xf
	v_fmac_f32_dpp v193, v193, v192 row_shr:2 row_mask:0xf bank_mask:0xf
	v_fmac_f32_dpp v195, v195, v194 row_shr:2 row_mask:0xf bank_mask:0xf
	v_fmac_f32_dpp v197, v197, v196 row_shr:2 row_mask:0xf bank_mask:0xf
	v_fmac_f32_dpp v199, v199, v198 row_shr:2 row_mask:0xf bank_mask:0xf
	v_mul_f32_dpp v192, v192, v192 row_shr:2 row_mask:0xf bank_mask:0xf
	v_mul_f32_dpp v194, v194, v194 row_shr:2 row_mask:0xf bank_mask:0xf
	v_mul_f32_dpp v196, v196, v196 row_shr:2 row_mask:0xf bank_mask:0xf
	v_mul_f32_dpp v198, v198, v198 row_shr:2 row_mask:0xf bank_mask:0xf
	v_fmac_f32_dpp v193, v193, v192 row_shr:4 row_mask:0xf bank_mask:0xf
	v_fmac_f32_dpp v195, v195, v194 row_shr:4 row_mask:0xf bank_mask:0xf
	v_fmac_f32_dpp v197, v197, v196 row_shr:4 row_mask:0xf bank_mask:0xf
	v_fmac_f32_dpp v199, v199, v198 row_shr:4 row_mask:0xf bank_mask:0xf
	v_mul_f32_dpp v192, v192, v192 row_shr:4 row_mask:0xf bank_mask:0xf
	v_mul_f32_dpp v194, v194, v194 row_shr:4 row_mask:0xf bank_mask:0xf
	v_mul_f32_dpp v196, v196, v196 row_shr:4 row_mask:0xf bank_mask:0xf
	v_mul_f32_dpp v198, v198, v198 row_shr:4 row_mask:0xf bank_mask:0xf
	v_fmac_f32_dpp v193, v193, v192 row_shr:8 row_mask:0xf bank_mask:0xf
	v_fmac_f32_dpp v195, v195, v194 row_shr:8 row_mask:0xf bank_mask:0xf
	v_fmac_f32_dpp v197, v197, v196 row_shr:8 row_mask:0xf bank_mask:0xf
	v_fmac_f32_dpp v199, v199, v198 row_shr:8 row_mask:0xf bank_mask:0xf
	v_mul_f32_dpp v192, v192, v192 row_shr:8 row_mask:0xf bank_mask:0xf
	v_mul_f32_dpp v194, v194, v194 row_shr:8 row_mask:0xf bank_mask:0xf
	v_mul_f32_dpp v196, v196, v196 row_shr:8 row_mask:0xf bank_mask:0xf
	v_mul_f32_dpp v198, v198, v198 row_shr:8 row_mask:0xf bank_mask:0xf
	v_fmac_f32_dpp v193, v193, v192 row_bcast:15 row_mask:0xa bank_mask:0xf
	v_fmac_f32_dpp v195, v195, v194 row_bcast:15 row_mask:0xa bank_mask:0xf
	v_fmac_f32_dpp v197, v197, v196 row_bcast:15 row_mask:0xa bank_mask:0xf
	v_fmac_f32_dpp v199, v199, v198 row_bcast:15 row_mask:0xa bank_mask:0xf
	v_mul_f32_dpp v192, v192, v192 row_bcast:15 row_mask:0xa bank_mask:0xf
	v_mul_f32_dpp v194, v194, v194 row_bcast:15 row_mask:0xa bank_mask:0xf
	v_mul_f32_dpp v196, v196, v196 row_bcast:15 row_mask:0xa bank_mask:0xf
	v_mul_f32_dpp v198, v198, v198 row_bcast:15 row_mask:0xa bank_mask:0xf
	v_fmac_f32_dpp v193, v193, v192 row_bcast:31 row_mask:0xc bank_mask:0xf
	v_fmac_f32_dpp v195, v195, v194 row_bcast:31 row_mask:0xc bank_mask:0xf
	v_fmac_f32_dpp v197, v197, v196 row_bcast:31 row_mask:0xc bank_mask:0xf
	v_fmac_f32_dpp v199, v199, v198 row_bcast:31 row_mask:0xc bank_mask:0xf
	v_mul_f32_dpp v192, v192, v192 row_bcast:31 row_mask:0xc bank_mask:0xf
	v_mul_f32_dpp v194, v194, v194 row_bcast:31 row_mask:0xc bank_mask:0xf
	v_mul_f32_dpp v196, v196, v196 row_bcast:31 row_mask:0xc bank_mask:0xf
	v_mul_f32_dpp v198, v198, v198 row_bcast:31 row_mask:0xc bank_mask:0xf
	v_mov_b32_dpp v201, v193 wave_shr:1 row_mask:0xf bank_mask:0xf
	v_mov_b32_dpp v203, v195 wave_shr:1 row_mask:0xf bank_mask:0xf
	v_mov_b32_dpp v205, v197 wave_shr:1 row_mask:0xf bank_mask:0xf
	v_mov_b32_dpp v207, v199 wave_shr:1 row_mask:0xf bank_mask:0xf
	v_mov_b32_dpp v200, v192 wave_shr:1 row_mask:0xf bank_mask:0xf
	v_mov_b32_dpp v202, v194 wave_shr:1 row_mask:0xf bank_mask:0xf
	v_mov_b32_dpp v204, v196 wave_shr:1 row_mask:0xf bank_mask:0xf
	v_mov_b32_dpp v206, v198 wave_shr:1 row_mask:0xf bank_mask:0xf
	ds_write_b64 v52, v[200:201]
	ds_write_b64 v52, v[202:203] offset:8
	ds_write_b64 v52, v[204:205] offset:16
	ds_write_b64 v52, v[206:207] offset:24
	s_and_saveexec_b64 s[30:31], s[50:51]
	s_cbranch_execz .Lscan_done
	s_and_b64 vcc, exec, s[70:71]
	s_cbranch_vccz .Lscan_ctx
	v_lshl_add_u64 v[208:209], v[46:47], 3, s[28:29]
	flat_store_dwordx2 v[208:209], v[192:193] sc1
	v_lshl_add_u64 v[208:209], v[48:49], 3, s[28:29]
	flat_store_dwordx2 v[208:209], v[194:195] offset:8 sc1
	flat_store_dwordx2 v[208:209], v[196:197] offset:16 sc1
	flat_store_dwordx2 v[208:209], v[198:199] offset:24 sc1
	s_branch .Lscan_done
.Lscan_ctx:
	v_add_u32_e32 v208, s7, v46
	v_ashrrev_i32_e32 v209, 31, v208
	v_lshl_add_u64 v[208:209], v[208:209], 2, s[66:67]
	global_store_dword v[208:209], v193, off
	v_add_u32_e32 v208, s7, v170
	v_ashrrev_i32_e32 v209, 31, v208
	v_lshl_add_u64 v[208:209], v[208:209], 2, s[66:67]
	global_store_dword v[208:209], v195, off
	v_add_u32_e32 v208, s7, v171
	v_ashrrev_i32_e32 v209, 31, v208
	v_lshl_add_u64 v[208:209], v[208:209], 2, s[66:67]
	global_store_dword v[208:209], v197, off
	v_add_u32_e32 v208, s7, v172
	v_ashrrev_i32_e32 v209, 31, v208
	v_lshl_add_u64 v[208:209], v[208:209], 2, s[66:67]
	global_store_dword v[208:209], v199, off
